# one static s_setprio 1 for the leading half (waves 0-3) over each GEMM phase, reset at the phase drain; no per-segment flips (on top of v52)
# baseline (speedup 1.0000x reference)
;     __host__ __device__ bool next(int i, Unit& u) const {
;         const long L = (long)i * G + c; if (L >= nwg) return false;
; template <class Epi, class Sched, bool ALIGN_EPI = false, bool SP2 = false>
; __device__ __forceinline__ void gemm_phase(PG8_LAS unsigned char* lds, const Gemm g, const Sched& S, const Epi& E) {
;     int tid_ = threadIdx.x; asm volatile("" : "+v"(tid_)); const int tid = tid_, wid = __builtin_amdgcn_readfirstlane(tid >> 6), lane = tid & 63, wr = wid >> 2, wc = wid & 3, fr = lane & 15, fq = lane >> 4;
;     const int K = g.K, nt = K / BK;
;     unsigned voffA[2], voffB[2];
; #pragma unroll
;     for (int i = 0; i < 2; ++i) { int R, C; stage_rc(tid * 16 + i * 8192, R, C); const int Rb = Epi::PERM ? ((R & ~31) + perm32(R & 31)) : R;
;         voffA[i] = (unsigned)(R * K + C) * 2u; voffB[i] = (unsigned)(Rb * K + C) * 2u; }
;     const size_t kstep = (size_t)(BK * 2);
;     const size_t hstep = (size_t)HALF * K * 2;
;     const size_t tstep = 2 * hstep;
;     const unsigned ldsw = (unsigned)wid * 1024u;
;     const int aoff = lds_byte(wr * 64 + fr, fq * 8), boff = lds_byte(wc * 32 + fr, fq * 8);
;     ...
;     Unit cur, nxt; int ui = 0;
;     if (!S.next(0, cur)) return;
;     f32x4 acc[2][2][4][2];
; #pragma unroll
;     for (int a = 0; a < 2; ++a)
; #pragma unroll
;         for (int b = 0; b < 2; ++b)
; #pragma unroll
;             for (int m = 0; m < 4; ++m)
; #pragma unroll
;                 for (int n = 0; n < 2; ++n) acc[a][b][m][n] = (f32x4){0.f, 0.f, 0.f, 0.f};
;     bf16x8 At[4][2], B0[2][2], B1[2][2];
;     const char* cA = (const char*)g.A + (size_t)cur.pm * tstep; const char* cB = (const char*)g.Bt + (size_t)cur.pn * tstep;
;     S.a_ready(cur);
;     if constexpr (SP2) {
;         PG8_STAGE(PG8_SB(0, 0), cB, voffB); PG8_STAGE(PG8_SB(0, 1), cB + hstep, voffB); PG8_STAGE(PG8_SA(0, 0), cA, voffA); PG8_STAGE(PG8_SA(0, 1), cA + hstep, voffA);
;         if (wr == 1) PG8_BAR;
;         PG8_WAIT_V(2); PG8_BAR;
;         PG8_STAGE(PG8_SB(1, 0), cB + kstep, voffB); PG8_STAGE(PG8_SA(1, 0), cA + kstep, voffA); PG8_STAGE(PG8_SB(1, 1), cB + hstep + kstep, voffB);
;         PG8_WAIT_V(6); PG8_BAR;
;     } else {
;         PG8_STAGE(PG8_SB(0, 0), cB, voffB); PG8_STAGE(PG8_SA(0, 0), cA, voffA); PG8_STAGE(PG8_SB(0, 1), cB + hstep, voffB); PG8_STAGE(PG8_SA(0, 1), cA + hstep, voffA);
;         if (wr == 1) PG8_BAR;
.LBB0_56:
	v_mov_b32_e32 v14, v187
	s_waitcnt lgkmcnt(0)
	s_barrier
	s_cmp_ge_i32 s84, s90
	v_readfirstlane_b32 s7, v14
	s_cbranch_scc1 .LBB0_72
	v_lshlrev_b32_e32 v0, 4, v14
	v_add_u32_e32 v1, 0x2000, v0
	v_ashrrev_i32_e32 v2, 31, v1
	v_lshrrev_b32_e32 v2, 22, v2
	v_add_u32_e32 v2, v1, v2
	v_ashrrev_i32_e32 v8, 10, v2
	v_mul_i32_i24_e32 v2, 0x400, v8
	v_sub_u32_e32 v1, v1, v2
	v_lshrrev_b32_e32 v2, 4, v1
	v_bitop3_b32 v1, v2, v1, 32 bitop3:0x6c
	v_ashrrev_i32_e32 v2, 31, v1
	v_lshrrev_b32_e32 v2, 26, v2
	s_mul_i32 s4, s25, 0xb00000
	v_add_u32_e32 v2, v1, v2
	v_lshlrev_b32_e32 v3, 3, v8
	s_ashr_i32 s5, s4, 31
	v_readlane_b32 s6, v249, 9
	v_ashrrev_i32_e32 v9, 6, v2
	v_and_b32_e32 v3, -16, v3
	s_add_u32 s28, s6, s4
	v_readlane_b32 s4, v249, 10
	v_add_u32_e32 v3, v9, v3
	s_addc_u32 s29, s4, s5
	v_and_b32_e32 v4, 3, v9
	s_mov_b32 s4, 0x1fffe0
	v_lshrrev_b32_e32 v5, 2, v3
	v_lshlrev_b32_e32 v6, 1, v3
	v_and_b32_e32 v2, 0xc0, v2
	v_and_or_b32 v4, v3, s4, v4
	v_and_b32_e32 v5, 4, v5
	v_and_b32_e32 v6, 24, v6
	v_sub_u32_e32 v1, v1, v2
	v_or3_b32 v4, v4, v5, v6
	v_lshlrev_b32_e32 v5, 5, v8
	v_ashrrev_i16_sdwa v1, v226, sext(v1) dst_sel:DWORD dst_unused:UNUSED_PAD src0_sel:DWORD src1_sel:BYTE_0
	v_and_b32_e32 v5, 32, v5
	v_bfe_i32 v10, v1, 0, 16
	v_add_lshl_u32 v1, v5, v10, 1
	v_lshl_add_u32 v130, v4, 11, v1
	v_lshl_add_u32 v132, v3, 11, v1
	v_bfe_i32 v1, v14, 27, 1
	v_lshrrev_b32_e32 v1, 22, v1
	v_add_u32_e32 v1, v0, v1
	v_and_b32_e32 v1, 0xfffffc00, v1
	v_sub_u32_e32 v0, v0, v1
	v_lshrrev_b32_e32 v1, 4, v0
	v_ashrrev_i32_e32 v2, 31, v14
	v_bitop3_b32 v0, v1, v0, 32 bitop3:0x6c
	v_lshrrev_b32_e32 v2, 26, v2
	v_ashrrev_i32_e32 v1, 31, v0
	v_add_u32_e32 v2, v14, v2
	v_lshrrev_b32_e32 v1, 26, v1
	v_ashrrev_i32_e32 v12, 6, v2
	v_add_u32_e32 v1, v0, v1
	v_lshlrev_b32_e32 v2, 3, v12
	v_ashrrev_i32_e32 v11, 6, v1
	v_and_b32_e32 v2, -16, v2
	v_add_u32_e32 v2, v11, v2
	v_and_b32_e32 v3, 3, v11
	s_ashr_i32 s9, s7, 6
	v_and_or_b32 v3, v2, s4, v3
	v_readlane_b32 s4, v249, 12
	s_ashr_i32 s8, s7, 8
	s_lshl_b32 s33, s9, 10
	v_readlane_b32 s5, v249, 13
	s_and_b64 s[4:5], s[4:5], exec
	s_cselect_b32 s4, s27, s26
	v_readlane_b32 s5, v248, 32
	s_mul_i32 s4, s4, s5
	v_readlane_b32 s5, v249, 11
	s_add_i32 s4, s4, s5
	s_mul_hi_i32 s5, s4, 0x2e8ba2e9
	s_lshr_b32 s6, s5, 31
	s_ashr_i32 s5, s5, 5
	v_lshrrev_b32_e32 v4, 2, v2
	v_lshlrev_b32_e32 v5, 1, v2
	v_and_b32_e32 v1, 0xc0, v1
	s_add_i32 s5, s5, s6
	v_and_b32_e32 v4, 4, v4
	v_and_b32_e32 v5, 24, v5
	v_sub_u32_e32 v0, v0, v1
	s_lshl_b32 s10, s5, 3
	v_or3_b32 v3, v3, v4, v5
	v_lshlrev_b32_e32 v4, 5, v12
	v_ashrrev_i16_sdwa v0, v226, sext(v0) dst_sel:DWORD dst_unused:UNUSED_PAD src0_sel:DWORD src1_sel:BYTE_0
	s_sub_i32 s6, s24, s10
	v_and_b32_e32 v4, 32, v4
	v_bfe_i32 v13, v0, 0, 16
	s_min_i32 s11, s6, 8
	v_add_lshl_u32 v0, v4, v13, 1
	s_sext_i32_i16 s6, s11
	v_lshl_add_u32 v64, v3, 11, v0
	v_lshl_add_u32 v134, v2, 11, v0
	v_cvt_f32_i32_e32 v0, s6
	s_mulk_i32 s5, 0xb0
	s_sub_i32 s12, s4, s5
	v_cvt_f32_i32_e32 v1, s12
	v_rcp_iflag_f32_e32 v2, v0
	s_xor_b32 s4, s12, s6
	s_ashr_i32 s4, s4, 30
	s_or_b32 s6, s4, 1
	v_mul_f32_e32 v2, v1, v2
	v_trunc_f32_e32 v2, v2
	v_fma_f32 v1, -v2, v0, v1
	v_cvt_i32_f32_e32 v2, v2
	v_cmp_ge_f32_e64 s[4:5], |v1|, |v0|
	s_and_b64 s[4:5], s[4:5], exec
	s_cselect_b32 s4, s6, 0
	v_readfirstlane_b32 s5, v2
	s_add_i32 s6, s5, s4
	s_mul_i32 s4, s6, s11
	s_sub_i32 s4, s12, s4
	s_sext_i32_i16 s4, s4
	s_add_i32 s16, s10, s4
	s_ashr_i32 s17, s16, 31
	s_bfe_i64 s[10:11], s[6:7], 0x100000
	s_lshl_b64 s[4:5], s[16:17], 19
	s_lshl_b64 s[10:11], s[10:11], 19
	s_add_u32 s20, s28, s10
	s_addc_u32 s21, s29, s11
	s_add_i32 s34, s33, 0
	s_add_i32 m0, s34, 0x10000
	v_mov_b32_e32 v131, v65
	global_load_lds_dwordx4 v64, s[20:21]
	s_add_i32 m0, s34, 0x12000
	s_add_u32 s10, s20, 0x40000
	global_load_lds_dwordx4 v130, s[20:21]
	s_addc_u32 s11, s21, 0
	s_add_i32 m0, s34, 0x14000
	v_mov_b32_e32 v135, v65
	global_load_lds_dwordx4 v64, s[10:11]
	s_add_i32 m0, s34, 0x16000
	s_add_u32 s18, s66, s4
	s_addc_u32 s19, s67, s5
	s_add_i32 s35, s34, 0x2000
	global_load_lds_dwordx4 v130, s[10:11]
	s_mov_b32 m0, s34
	s_add_u32 s4, s18, 0x40000
	global_load_lds_dwordx4 v134, s[18:19]
	s_mov_b32 m0, s35
	s_addc_u32 s5, s19, 0
	s_add_i32 s36, s34, 0x4000
	global_load_lds_dwordx4 v132, s[18:19]
	s_mov_b32 m0, s36
	s_add_i32 s37, s34, 0x6000
	global_load_lds_dwordx4 v134, s[4:5]
	s_mov_b32 m0, s37
	v_mov_b32_e32 v133, v65
	global_load_lds_dwordx4 v132, s[4:5]
	s_cmp_eq_u32 s8, 1
	v_lshl_add_u64 v[6:7], s[20:21], 0, v[64:65]
	v_lshl_add_u64 v[4:5], s[20:21], 0, v[130:131]
	v_lshl_add_u64 v[0:1], s[18:19], 0, v[134:135]
	s_cselect_b64 s[4:5], -1, 0
	s_cmp_lg_u32 s8, 1
	v_lshl_add_u64 v[2:3], s[18:19], 0, v[132:133]
	s_mov_b64 s[10:11], 0x80
	s_setprio 1
	s_cbranch_scc1 .LBB0_59
	s_setprio 0
	s_barrier

; #define PG8_WAIT_V(n) asm volatile("s_waitcnt vmcnt(" #n ")" ::: "memory")
; #define PG8_BAR __builtin_amdgcn_s_barrier()
; template <class Epi, class Sched, bool ALIGN_EPI = false, bool SP2 = false>
; __device__ __forceinline__ void gemm_phase(PG8_LAS unsigned char* lds, const Gemm g, const Sched& S, const Epi& E) {
;     ...
;     PG8_WAIT_V(0);
;     if constexpr (!ALIGN_EPI) { if (wr == 0) PG8_BAR; }
;     PG8_BAR;
.LBB0_71:
	s_setprio 0
	s_waitcnt vmcnt(0)
	v_readlane_b32 s34, v247, 12
	v_readlane_b32 s36, v247, 14
	v_readlane_b32 s35, v247, 13
	v_readlane_b32 s37, v247, 15
	s_movk_i32 s38, 0x2000
	v_readlane_b32 s39, v247, 54
	s_barrier

; #define PG8_WAIT_V(n) asm volatile("s_waitcnt vmcnt(" #n ")" ::: "memory")
; #define PG8_BAR __builtin_amdgcn_s_barrier()
; template <class Epi, class Sched, bool ALIGN_EPI = false, bool SP2 = false>
; __device__ __forceinline__ void gemm_phase(PG8_LAS unsigned char* lds, const Gemm g, const Sched& S, const Epi& E) {
;     int tid_ = threadIdx.x; asm volatile("" : "+v"(tid_)); const int tid = tid_, wid = __builtin_amdgcn_readfirstlane(tid >> 6), lane = tid & 63, wr = wid >> 2, wc = wid & 3, fr = lane & 15, fq = lane >> 4;
;     const int K = g.K, nt = K / BK;
;     unsigned voffA[2], voffB[2];
; #pragma unroll
;     for (int i = 0; i < 2; ++i) { int R, C; stage_rc(tid * 16 + i * 8192, R, C); const int Rb = Epi::PERM ? ((R & ~31) + perm32(R & 31)) : R;
;         voffA[i] = (unsigned)(R * K + C) * 2u; voffB[i] = (unsigned)(Rb * K + C) * 2u; }
;     const size_t kstep = (size_t)(BK * 2);
;     const size_t hstep = (size_t)HALF * K * 2;
;     const size_t tstep = 2 * hstep;
;     const unsigned ldsw = (unsigned)wid * 1024u;
;     const int aoff = lds_byte(wr * 64 + fr, fq * 8), boff = lds_byte(wc * 32 + fr, fq * 8);
;     ...
;     Unit cur, nxt; int ui = 0;
;     if (!S.next(0, cur)) return;
;     f32x4 acc[2][2][4][2];
; #pragma unroll
;     for (int a = 0; a < 2; ++a)
; #pragma unroll
;         for (int b = 0; b < 2; ++b)
; #pragma unroll
;             for (int m = 0; m < 4; ++m)
; #pragma unroll
;                 for (int n = 0; n < 2; ++n) acc[a][b][m][n] = (f32x4){0.f, 0.f, 0.f, 0.f};
;     bf16x8 At[4][2], B0[2][2], B1[2][2];
;     const char* cA = (const char*)g.A + (size_t)cur.pm * tstep; const char* cB = (const char*)g.Bt + (size_t)cur.pn * tstep;
;     S.a_ready(cur);
;     if constexpr (SP2) {
;         PG8_STAGE(PG8_SB(0, 0), cB, voffB); PG8_STAGE(PG8_SB(0, 1), cB + hstep, voffB); PG8_STAGE(PG8_SA(0, 0), cA, voffA); PG8_STAGE(PG8_SA(0, 1), cA + hstep, voffA);
;         if (wr == 1) PG8_BAR;
;         PG8_WAIT_V(2); PG8_BAR;
;         PG8_STAGE(PG8_SB(1, 0), cB + kstep, voffB); PG8_STAGE(PG8_SA(1, 0), cA + kstep, voffA); PG8_STAGE(PG8_SB(1, 1), cB + hstep + kstep, voffB);
;         PG8_WAIT_V(6); PG8_BAR;
;     } else {
;         PG8_STAGE(PG8_SB(0, 0), cB, voffB); PG8_STAGE(PG8_SA(0, 0), cA, voffA); PG8_STAGE(PG8_SB(0, 1), cB + hstep, voffB); PG8_STAGE(PG8_SA(0, 1), cA + hstep, voffA);
;         if (wr == 1) PG8_BAR;
.LBB0_84:
	s_andn2_b64 vcc, exec, s[2:3]
	s_cbranch_vccnz .LBB0_223
	v_bfe_i32 v2, v18, 27, 1
	v_lshlrev_b32_e32 v0, 4, v18
	v_lshrrev_b32_e32 v2, 22, v2
	v_add_u32_e32 v2, v0, v2
	v_and_b32_e32 v2, 0xfffffc00, v2
	v_sub_u32_e32 v2, v0, v2
	s_waitcnt lgkmcnt(0)
	v_ashrrev_i32_e32 v1, 31, v18
	v_lshrrev_b32_e32 v3, 4, v2
	v_lshrrev_b32_e32 v1, 26, v1
	v_bitop3_b32 v2, v3, v2, 32 bitop3:0x6c
	v_add_u32_e32 v1, v18, v1
	v_ashrrev_i32_e32 v4, 31, v2
	v_ashrrev_i32_e32 v1, 6, v1
	v_lshrrev_b32_e32 v4, 26, v4
	v_lshlrev_b32_e32 v3, 3, v1
	v_add_u32_e32 v4, v2, v4
	v_and_b32_e32 v3, -16, v3
	v_ashrrev_i32_e32 v5, 6, v4
	v_lshlrev_b32_e32 v1, 5, v1
	v_add_u32_e32 v3, v5, v3
	v_and_b32_e32 v12, 32, v1
	v_and_b32_e32 v1, 0xc0, v4
	v_sub_u32_e32 v1, v2, v1
	v_lshlrev_b32_e32 v2, 1, v3
	v_lshrrev_b32_e32 v4, 2, v3
	v_and_b32_e32 v5, 3, v5
	s_mov_b32 s2, 0x7fffffe0
	v_ashrrev_i16_sdwa v1, v226, sext(v1) dst_sel:DWORD dst_unused:UNUSED_PAD src0_sel:DWORD src1_sel:BYTE_0
	v_and_b32_e32 v2, 24, v2
	v_and_b32_e32 v4, 4, v4
	v_and_or_b32 v5, v3, s2, v5
	v_bfe_i32 v13, v1, 0, 16
	v_or3_b32 v2, v5, v4, v2
	v_add_u32_e32 v1, v12, v13
	v_mul_lo_u32 v14, v3, s12
	v_mul_lo_u32 v2, v2, s12
	v_add_u32_e32 v0, 0x2000, v0
	v_add_lshl_u32 v188, v1, v14, 1
	v_add_lshl_u32 v190, v2, v1, 1
	v_ashrrev_i32_e32 v1, 31, v0
	v_lshrrev_b32_e32 v1, 22, v1
	v_add_u32_e32 v1, v0, v1
	v_ashrrev_i32_e32 v1, 10, v1
	v_mul_i32_i24_e32 v2, 0x400, v1
	v_sub_u32_e32 v0, v0, v2
	v_lshrrev_b32_e32 v2, 4, v0
	v_bitop3_b32 v0, v2, v0, 32 bitop3:0x6c
	v_ashrrev_i32_e32 v3, 31, v0
	v_lshrrev_b32_e32 v3, 26, v3
	v_lshlrev_b32_e32 v2, 3, v1
	v_add_u32_e32 v3, v0, v3
	v_and_b32_e32 v2, -16, v2
	v_ashrrev_i32_e32 v4, 6, v3
	s_ashr_i32 s13, s7, 6
	v_add_u32_e32 v2, v4, v2
	v_and_b32_e32 v4, 3, v4
	v_and_or_b32 v4, v2, s2, v4
	s_ashr_i32 s14, s7, 8
	s_lshl_b32 s2, s12, 8
	s_lshl_b32 s26, s12, 9
	s_lshl_b32 s27, s13, 10
	v_lshlrev_b32_e32 v1, 5, v1
	s_and_b64 s[8:9], s[0:1], exec
	v_and_b32_e32 v15, 32, v1
	v_and_b32_e32 v1, 0xc0, v3
	s_mul_i32 s9, s26, s50
	v_sub_u32_e32 v0, v0, v1
	v_lshlrev_b32_e32 v1, 1, v2
	v_lshrrev_b32_e32 v3, 2, v2
	s_cselect_b32 s28, s76, s79
	s_cselect_b32 s29, s75, s78
	s_mul_hi_i32 s8, s26, s50
	s_add_u32 s22, s4, s9
	v_ashrrev_i16_sdwa v0, v226, sext(v0) dst_sel:DWORD dst_unused:UNUSED_PAD src0_sel:DWORD src1_sel:BYTE_0
	v_and_b32_e32 v1, 24, v1
	v_and_b32_e32 v3, 4, v3
	s_addc_u32 s23, s5, s8
	s_add_i32 s33, s27, 0
	v_bfe_i32 v16, v0, 0, 16
	v_or3_b32 v1, v4, v3, v1
	s_add_i32 m0, s33, 0x10000
	v_add_u32_e32 v0, v15, v16
	v_mul_lo_u32 v1, v1, s12
	global_load_lds_dwordx4 v190, s[22:23]
	s_add_i32 m0, s33, 0x12000
	v_add_lshl_u32 v194, v1, v0, 1
	s_add_u32 s8, s22, s2
	global_load_lds_dwordx4 v194, s[22:23]
	s_addc_u32 s9, s23, 0
	s_add_i32 m0, s33, 0x14000
	s_mul_i32 s11, s26, s51
	global_load_lds_dwordx4 v190, s[8:9]
	s_add_i32 m0, s33, 0x16000
	s_mul_hi_i32 s10, s26, s51
	s_add_u32 s18, s29, s11
	v_mov_b32_e32 v191, v65
	v_mov_b32_e32 v195, v65
	s_addc_u32 s19, s28, s10
	s_add_i32 s34, s33, 0x2000
	v_mul_lo_u32 v17, v2, s12
	v_lshl_add_u64 v[4:5], s[8:9], 0, v[190:191]
	v_lshl_add_u64 v[6:7], s[8:9], 0, v[194:195]
	global_load_lds_dwordx4 v194, s[8:9]
	s_mov_b32 m0, s33
	s_add_u32 s8, s18, s2
	v_add_lshl_u32 v192, v0, v17, 1
	global_load_lds_dwordx4 v188, s[18:19]
	s_mov_b32 m0, s34
	s_addc_u32 s9, s19, 0
	s_add_i32 s35, s33, 0x4000
	global_load_lds_dwordx4 v192, s[18:19]
	s_mov_b32 m0, s35
	s_add_i32 s36, s33, 0x6000
	global_load_lds_dwordx4 v188, s[8:9]
	s_mov_b32 m0, s36
	v_mov_b32_e32 v189, v65
	global_load_lds_dwordx4 v192, s[8:9]
	v_mov_b32_e32 v193, v65
	s_cmp_eq_u32 s14, 1
	s_mov_b32 s3, s91
	v_lshl_add_u64 v[0:1], s[22:23], 0, v[190:191]
	v_lshl_add_u64 v[2:3], s[22:23], 0, v[194:195]
	v_lshl_add_u64 v[8:9], s[18:19], 0, v[188:189]
	v_lshl_add_u64 v[10:11], s[18:19], 0, v[192:193]
	s_cselect_b64 s[8:9], -1, 0
	s_cmp_lg_u32 s14, 1
	s_mov_b64 s[16:17], 0x80
	s_setprio 1
	s_cbranch_scc1 .LBB0_87
	s_setprio 0
	s_barrier

;     __host__ __device__ bool next(int i, Unit& u) const {
;         const long L = (long)i * G + c; if (L >= nwg) return false;
; template <class Epi, class Sched, bool ALIGN_EPI = false, bool SP2 = false>
; __device__ __forceinline__ void gemm_phase(PG8_LAS unsigned char* lds, const Gemm g, const Sched& S, const Epi& E) {
;     int tid_ = threadIdx.x; asm volatile("" : "+v"(tid_)); const int tid = tid_, wid = __builtin_amdgcn_readfirstlane(tid >> 6), lane = tid & 63, wr = wid >> 2, wc = wid & 3, fr = lane & 15, fq = lane >> 4;
;     const int K = g.K, nt = K / BK;
;     unsigned voffA[2], voffB[2];
; #pragma unroll
;     for (int i = 0; i < 2; ++i) { int R, C; stage_rc(tid * 16 + i * 8192, R, C); const int Rb = Epi::PERM ? ((R & ~31) + perm32(R & 31)) : R;
;         voffA[i] = (unsigned)(R * K + C) * 2u; voffB[i] = (unsigned)(Rb * K + C) * 2u; }
;     const size_t kstep = (size_t)(BK * 2);
;     const size_t hstep = (size_t)HALF * K * 2;
;     const size_t tstep = 2 * hstep;
;     const unsigned ldsw = (unsigned)wid * 1024u;
;     const int aoff = lds_byte(wr * 64 + fr, fq * 8), boff = lds_byte(wc * 32 + fr, fq * 8);
;     ...
;     Unit cur, nxt; int ui = 0;
;     if (!S.next(0, cur)) return;
;     f32x4 acc[2][2][4][2];
; #pragma unroll
;     for (int a = 0; a < 2; ++a)
; #pragma unroll
;         for (int b = 0; b < 2; ++b)
; #pragma unroll
;             for (int m = 0; m < 4; ++m)
; #pragma unroll
;                 for (int n = 0; n < 2; ++n) acc[a][b][m][n] = (f32x4){0.f, 0.f, 0.f, 0.f};
;     bf16x8 At[4][2], B0[2][2], B1[2][2];
;     const char* cA = (const char*)g.A + (size_t)cur.pm * tstep; const char* cB = (const char*)g.Bt + (size_t)cur.pn * tstep;
;     S.a_ready(cur);
;     if constexpr (SP2) {
;         PG8_STAGE(PG8_SB(0, 0), cB, voffB); PG8_STAGE(PG8_SB(0, 1), cB + hstep, voffB); PG8_STAGE(PG8_SA(0, 0), cA, voffA); PG8_STAGE(PG8_SA(0, 1), cA + hstep, voffA);
;         if (wr == 1) PG8_BAR;
;         PG8_WAIT_V(2); PG8_BAR;
;         PG8_STAGE(PG8_SB(1, 0), cB + kstep, voffB); PG8_STAGE(PG8_SA(1, 0), cA + kstep, voffA); PG8_STAGE(PG8_SB(1, 1), cB + hstep + kstep, voffB);
;         PG8_WAIT_V(6); PG8_BAR;
;     } else {
;         PG8_STAGE(PG8_SB(0, 0), cB, voffB); PG8_STAGE(PG8_SA(0, 0), cA, voffA); PG8_STAGE(PG8_SB(0, 1), cB + hstep, voffB); PG8_STAGE(PG8_SA(0, 1), cA + hstep, voffA);
;         if (wr == 1) PG8_BAR;
.LBB0_243:
	v_mov_b32_e32 v14, v187
	s_waitcnt vmcnt(0) lgkmcnt(0)
	s_barrier
	s_cmp_ge_i32 s84, s90
	v_readfirstlane_b32 s4, v14
	s_cbranch_scc1 .LBB0_263
	v_lshlrev_b32_e32 v0, 4, v14
	v_add_u32_e32 v1, 0x2000, v0
	v_ashrrev_i32_e32 v2, 31, v1
	v_lshrrev_b32_e32 v2, 22, v2
	v_add_u32_e32 v2, v1, v2
	v_ashrrev_i32_e32 v8, 10, v2
	v_mul_i32_i24_e32 v2, 0x400, v8
	v_sub_u32_e32 v1, v1, v2
	v_lshrrev_b32_e32 v2, 4, v1
	v_bitop3_b32 v1, v2, v1, 32 bitop3:0x6c
	v_ashrrev_i32_e32 v2, 31, v1
	v_readlane_b32 s0, v247, 48
	v_lshrrev_b32_e32 v2, 26, v2
	v_readlane_b32 s1, v247, 49
	s_mul_i32 s0, s0, 0x600000
	v_add_u32_e32 v2, v1, v2
	v_lshlrev_b32_e32 v3, 3, v8
	s_ashr_i32 s1, s0, 31
	v_readlane_b32 s2, v249, 26
	v_ashrrev_i32_e32 v9, 6, v2
	v_and_b32_e32 v3, -16, v3
	s_add_u32 s25, s2, s0
	v_readlane_b32 s0, v249, 27
	v_add_u32_e32 v3, v9, v3
	s_addc_u32 s26, s0, s1
	v_and_b32_e32 v4, 3, v9
	s_mov_b32 s0, 0x1fffe0
	v_lshrrev_b32_e32 v5, 2, v3
	v_lshlrev_b32_e32 v6, 1, v3
	v_and_b32_e32 v2, 0xc0, v2
	v_and_or_b32 v4, v3, s0, v4
	v_and_b32_e32 v5, 4, v5
	v_and_b32_e32 v6, 24, v6
	v_sub_u32_e32 v1, v1, v2
	v_or3_b32 v4, v4, v5, v6
	v_lshlrev_b32_e32 v5, 5, v8
	v_ashrrev_i16_sdwa v1, v226, sext(v1) dst_sel:DWORD dst_unused:UNUSED_PAD src0_sel:DWORD src1_sel:BYTE_0
	v_and_b32_e32 v5, 32, v5
	v_bfe_i32 v10, v1, 0, 16
	v_add_lshl_u32 v1, v5, v10, 1
	v_lshl_add_u32 v130, v4, 11, v1
	v_lshl_add_u32 v132, v3, 11, v1
	v_bfe_i32 v1, v14, 27, 1
	v_lshrrev_b32_e32 v1, 22, v1
	v_add_u32_e32 v1, v0, v1
	v_and_b32_e32 v1, 0xfffffc00, v1
	v_sub_u32_e32 v0, v0, v1
	v_lshrrev_b32_e32 v1, 4, v0
	v_ashrrev_i32_e32 v2, 31, v14
	v_bitop3_b32 v0, v1, v0, 32 bitop3:0x6c
	v_lshrrev_b32_e32 v2, 26, v2
	v_ashrrev_i32_e32 v1, 31, v0
	v_add_u32_e32 v2, v14, v2
	v_lshrrev_b32_e32 v1, 26, v1
	v_ashrrev_i32_e32 v12, 6, v2
	v_add_u32_e32 v1, v0, v1
	v_lshlrev_b32_e32 v2, 3, v12
	v_ashrrev_i32_e32 v11, 6, v1
	v_and_b32_e32 v2, -16, v2
	v_add_u32_e32 v2, v11, v2
	v_and_b32_e32 v3, 3, v11
	s_ashr_i32 s5, s4, 6
	v_and_or_b32 v3, v2, s0, v3
	v_readlane_b32 s0, v249, 12
	s_ashr_i32 s6, s4, 8
	s_lshl_b32 s27, s5, 10
	v_readlane_b32 s1, v249, 13
	s_and_b64 s[0:1], s[0:1], exec
	s_cselect_b32 s0, s24, s23
	v_readlane_b32 s1, v248, 32
	s_mul_i32 s0, s0, s1
	v_readlane_b32 s1, v249, 11
	s_add_i32 s0, s0, s1
	s_mul_hi_i32 s1, s0, 0x2aaaaaab
	s_lshr_b32 s2, s1, 31
	s_ashr_i32 s1, s1, 4
	v_lshrrev_b32_e32 v4, 2, v2
	v_lshlrev_b32_e32 v5, 1, v2
	v_and_b32_e32 v1, 0xc0, v1
	s_add_i32 s1, s1, s2
	v_and_b32_e32 v4, 4, v4
	v_and_b32_e32 v5, 24, v5
	v_sub_u32_e32 v0, v0, v1
	s_lshl_b32 s3, s1, 3
	v_or3_b32 v3, v3, v4, v5
	v_lshlrev_b32_e32 v4, 5, v12
	v_ashrrev_i16_sdwa v0, v226, sext(v0) dst_sel:DWORD dst_unused:UNUSED_PAD src0_sel:DWORD src1_sel:BYTE_0
	s_sub_i32 s2, s22, s3
	v_and_b32_e32 v4, 32, v4
	v_bfe_i32 v13, v0, 0, 16
	s_min_i32 s7, s2, 8
	v_add_lshl_u32 v0, v4, v13, 1
	s_sext_i32_i16 s2, s7
	v_lshl_add_u32 v134, v3, 11, v0
	v_lshl_add_u32 v136, v2, 11, v0
	v_cvt_f32_i32_e32 v0, s2
	s_mulk_i32 s1, 0x60
	s_sub_i32 s8, s0, s1
	v_cvt_f32_i32_e32 v1, s8
	v_rcp_iflag_f32_e32 v2, v0
	s_xor_b32 s0, s8, s2
	s_ashr_i32 s0, s0, 30
	s_or_b32 s2, s0, 1
	v_mul_f32_e32 v2, v1, v2
	v_trunc_f32_e32 v2, v2
	v_fma_f32 v1, -v2, v0, v1
	v_cvt_i32_f32_e32 v2, v2
	v_cmp_ge_f32_e64 s[0:1], |v1|, |v0|
	s_and_b64 s[0:1], s[0:1], exec
	s_cselect_b32 s0, s2, 0
	v_readfirstlane_b32 s1, v2
	s_add_i32 s2, s1, s0
	s_mul_i32 s0, s2, s7
	s_sub_i32 s0, s8, s0
	s_sext_i32_i16 s0, s0
	s_add_i32 s14, s3, s0
	s_ashr_i32 s15, s14, 31
	s_bfe_i64 s[8:9], s[2:3], 0x100000
	s_lshl_b64 s[0:1], s[14:15], 19
	s_lshl_b64 s[8:9], s[8:9], 19
	s_add_u32 s18, s25, s8
	s_addc_u32 s19, s26, s9
	s_add_i32 s28, s27, 0
	s_add_i32 m0, s28, 0x10000
	v_mov_b32_e32 v135, v65
	global_load_lds_dwordx4 v134, s[18:19]
	s_add_i32 m0, s28, 0x12000
	s_add_u32 s8, s18, 0x40000
	global_load_lds_dwordx4 v130, s[18:19]
	s_addc_u32 s9, s19, 0
	s_add_i32 m0, s28, 0x14000
	v_mov_b32_e32 v131, v65
	global_load_lds_dwordx4 v134, s[8:9]
	s_add_i32 m0, s28, 0x16000
	s_add_u32 s16, s66, s0
	s_addc_u32 s17, s67, s1
	s_add_i32 s29, s28, 0x2000
	global_load_lds_dwordx4 v130, s[8:9]
	s_mov_b32 m0, s28
	s_add_u32 s0, s16, 0x40000
	global_load_lds_dwordx4 v136, s[16:17]
	s_mov_b32 m0, s29
	s_addc_u32 s1, s17, 0
	s_add_i32 s33, s28, 0x4000
	global_load_lds_dwordx4 v132, s[16:17]
	s_mov_b32 m0, s33
	s_add_i32 s34, s28, 0x6000
	global_load_lds_dwordx4 v136, s[0:1]
	s_mov_b32 m0, s34
	v_mov_b32_e32 v137, v65
	global_load_lds_dwordx4 v132, s[0:1]
	v_mov_b32_e32 v133, v65
	s_cmp_eq_u32 s6, 1
	v_lshl_add_u64 v[6:7], s[18:19], 0, v[134:135]
	v_lshl_add_u64 v[4:5], s[18:19], 0, v[130:131]
	v_lshl_add_u64 v[0:1], s[16:17], 0, v[136:137]
	s_cselect_b64 s[0:1], -1, 0
	s_cmp_lg_u32 s6, 1
	v_lshl_add_u64 v[2:3], s[16:17], 0, v[132:133]
	s_mov_b64 s[8:9], 0x80
	v_readlane_b32 s3, v247, 52
	s_setprio 1
	s_cbranch_scc1 .LBB0_246
	s_setprio 0
	s_barrier

; #define PG8_WAIT_V(n) asm volatile("s_waitcnt vmcnt(" #n ")" ::: "memory")
; #define PG8_BAR __builtin_amdgcn_s_barrier()
; template <class Epi, class Sched, bool ALIGN_EPI = false, bool SP2 = false>
; __device__ __forceinline__ void gemm_phase(PG8_LAS unsigned char* lds, const Gemm g, const Sched& S, const Epi& E) {
;     int tid_ = threadIdx.x; asm volatile("" : "+v"(tid_)); const int tid = tid_, wid = __builtin_amdgcn_readfirstlane(tid >> 6), lane = tid & 63, wr = wid >> 2, wc = wid & 3, fr = lane & 15, fq = lane >> 4;
;     const int K = g.K, nt = K / BK;
;     unsigned voffA[2], voffB[2];
; #pragma unroll
;     for (int i = 0; i < 2; ++i) { int R, C; stage_rc(tid * 16 + i * 8192, R, C); const int Rb = Epi::PERM ? ((R & ~31) + perm32(R & 31)) : R;
;         voffA[i] = (unsigned)(R * K + C) * 2u; voffB[i] = (unsigned)(Rb * K + C) * 2u; }
;     const size_t kstep = (size_t)(BK * 2);
;     const size_t hstep = (size_t)HALF * K * 2;
;     const size_t tstep = 2 * hstep;
;     const unsigned ldsw = (unsigned)wid * 1024u;
;     const int aoff = lds_byte(wr * 64 + fr, fq * 8), boff = lds_byte(wc * 32 + fr, fq * 8);
;     ...
;     Unit cur, nxt; int ui = 0;
;     if (!S.next(0, cur)) return;
;     f32x4 acc[2][2][4][2];
; #pragma unroll
;     for (int a = 0; a < 2; ++a)
; #pragma unroll
;         for (int b = 0; b < 2; ++b)
; #pragma unroll
;             for (int m = 0; m < 4; ++m)
; #pragma unroll
;                 for (int n = 0; n < 2; ++n) acc[a][b][m][n] = (f32x4){0.f, 0.f, 0.f, 0.f};
;     bf16x8 At[4][2], B0[2][2], B1[2][2];
;     const char* cA = (const char*)g.A + (size_t)cur.pm * tstep; const char* cB = (const char*)g.Bt + (size_t)cur.pn * tstep;
;     S.a_ready(cur);
;     if constexpr (SP2) {
;         PG8_STAGE(PG8_SB(0, 0), cB, voffB); PG8_STAGE(PG8_SB(0, 1), cB + hstep, voffB); PG8_STAGE(PG8_SA(0, 0), cA, voffA); PG8_STAGE(PG8_SA(0, 1), cA + hstep, voffA);
;         if (wr == 1) PG8_BAR;
;         PG8_WAIT_V(2); PG8_BAR;
;         PG8_STAGE(PG8_SB(1, 0), cB + kstep, voffB); PG8_STAGE(PG8_SA(1, 0), cA + kstep, voffA); PG8_STAGE(PG8_SB(1, 1), cB + hstep + kstep, voffB);
;         PG8_WAIT_V(6); PG8_BAR;
;     } else {
;         PG8_STAGE(PG8_SB(0, 0), cB, voffB); PG8_STAGE(PG8_SA(0, 0), cA, voffA); PG8_STAGE(PG8_SB(0, 1), cB + hstep, voffB); PG8_STAGE(PG8_SA(0, 1), cA + hstep, voffA);
;         if (wr == 1) PG8_BAR;
.LBB0_464:
	s_andn2_b64 vcc, exec, s[0:1]
	s_cbranch_vccnz .LBB0_580
	v_ashrrev_i32_e32 v1, 31, v8
	v_lshrrev_b32_e32 v1, 26, v1
	v_add_u32_e32 v1, v8, v1
	v_ashrrev_i32_e32 v9, 6, v1
	v_bfe_i32 v1, v8, 27, 1
	v_lshlrev_b32_e32 v0, 4, v8
	v_lshrrev_b32_e32 v1, 22, v1
	v_add_u32_e32 v1, v0, v1
	v_and_b32_e32 v1, 0xfffffc00, v1
	v_sub_u32_e32 v1, v0, v1
	v_lshrrev_b32_e32 v2, 4, v1
	v_bitop3_b32 v1, v2, v1, 32 bitop3:0x6c
	v_ashrrev_i32_e32 v3, 31, v1
	v_readlane_b32 s0, v247, 48
	v_lshrrev_b32_e32 v3, 26, v3
	v_readlane_b32 s1, v247, 49
	v_add_u32_e32 v3, v1, v3
	s_ashr_i32 s1, s0, 31
	v_lshlrev_b32_e32 v2, 3, v9
	v_ashrrev_i32_e32 v10, 6, v3
	v_and_b32_e32 v3, 0xc0, v3
	s_mov_b32 s26, s0
	s_lshl_b64 s[0:1], s[0:1], 23
	v_readlane_b32 s3, v249, 30
	v_and_b32_e32 v2, -16, v2
	v_sub_u32_e32 v1, v1, v3
	s_add_u32 s13, s3, s0
	v_readlane_b32 s0, v249, 31
	v_add_u32_e32 v2, v10, v2
	v_ashrrev_i16_sdwa v1, v226, sext(v1) dst_sel:DWORD dst_unused:UNUSED_PAD src0_sel:DWORD src1_sel:BYTE_0
	s_addc_u32 s14, s0, s1
	v_lshlrev_b32_e32 v4, 5, v9
	v_bfe_i32 v11, v1, 0, 16
	v_lshlrev_b32_e32 v1, 1, v2
	v_lshrrev_b32_e32 v3, 2, v2
	v_and_b32_e32 v5, 3, v10
	s_mov_b32 s0, 0x1fffe0
	v_and_b32_e32 v4, 32, v4
	v_and_b32_e32 v1, 24, v1
	v_and_b32_e32 v3, 4, v3
	v_and_or_b32 v5, v2, s0, v5
	v_or3_b32 v1, v5, v3, v1
	v_add_lshl_u32 v3, v4, v11, 1
	v_add_u32_e32 v0, 0x2000, v0
	v_lshl_add_u32 v148, v1, 11, v3
	v_ashrrev_i32_e32 v1, 31, v0
	v_lshrrev_b32_e32 v1, 22, v1
	v_add_u32_e32 v1, v0, v1
	v_ashrrev_i32_e32 v12, 10, v1
	v_mul_i32_i24_e32 v1, 0x400, v12
	v_sub_u32_e32 v0, v0, v1
	v_lshrrev_b32_e32 v1, 4, v0
	v_bitop3_b32 v0, v1, v0, 32 bitop3:0x6c
	v_lshl_add_u32 v146, v2, 11, v3
	v_ashrrev_i32_e32 v2, 31, v0
	v_lshrrev_b32_e32 v2, 26, v2
	v_lshlrev_b32_e32 v1, 3, v12
	v_add_u32_e32 v2, v0, v2
	v_and_b32_e32 v1, -16, v1
	v_ashrrev_i32_e32 v13, 6, v2
	v_add_u32_e32 v1, v13, v1
	v_and_b32_e32 v2, 0xc0, v2
	v_and_b32_e32 v4, 3, v13
	s_ashr_i32 s20, s10, 6
	s_ashr_i32 s3, s2, 31
	s_ashr_i32 s5, s4, 31
	s_ashr_i32 s11, s10, 8
	v_sub_u32_e32 v0, v0, v2
	v_and_or_b32 v4, v1, s0, v4
	s_lshl_b32 s15, s20, 10
	s_lshl_b64 s[0:1], s[2:3], 19
	s_lshl_b64 s[6:7], s[4:5], 19
	v_ashrrev_i16_sdwa v0, v226, sext(v0) dst_sel:DWORD dst_unused:UNUSED_PAD src0_sel:DWORD src1_sel:BYTE_0
	s_add_u32 s8, s13, s6
	v_lshlrev_b32_e32 v3, 5, v12
	v_bfe_i32 v14, v0, 0, 16
	v_lshlrev_b32_e32 v0, 1, v1
	v_lshrrev_b32_e32 v2, 2, v1
	s_addc_u32 s9, s14, s7
	s_add_i32 s16, s15, 0
	v_and_b32_e32 v3, 32, v3
	v_and_b32_e32 v0, 24, v0
	v_and_b32_e32 v2, 4, v2
	s_add_i32 m0, s16, 0x10000
	v_or3_b32 v0, v4, v2, v0
	v_add_lshl_u32 v2, v3, v14, 1
	global_load_lds_dwordx4 v148, s[8:9]
	s_add_i32 m0, s16, 0x12000
	v_lshl_add_u32 v152, v0, 11, v2
	s_add_u32 s6, s8, 0x40000
	global_load_lds_dwordx4 v152, s[8:9]
	s_addc_u32 s7, s9, 0
	s_add_i32 m0, s16, 0x14000
	v_lshl_add_u32 v150, v1, 11, v2
	global_load_lds_dwordx4 v148, s[6:7]
	s_add_i32 m0, s16, 0x16000
	v_mov_b32_e32 v149, v65
	global_load_lds_dwordx4 v152, s[6:7]
	s_add_u32 s6, s66, s0
	s_addc_u32 s7, s67, s1
	s_add_i32 s17, s16, 0x2000
	s_mov_b32 m0, s16
	s_add_u32 s0, s6, 0x40000
	global_load_lds_dwordx4 v146, s[6:7]
	s_mov_b32 m0, s17
	s_addc_u32 s1, s7, 0
	s_add_i32 s18, s16, 0x4000
	global_load_lds_dwordx4 v150, s[6:7]
	s_mov_b32 m0, s18
	s_add_i32 s19, s16, 0x6000
	global_load_lds_dwordx4 v146, s[0:1]
	s_mov_b32 m0, s19
	v_mov_b32_e32 v153, v65
	global_load_lds_dwordx4 v150, s[0:1]
	v_mov_b32_e32 v147, v65
	v_mov_b32_e32 v151, v65
	s_cmp_eq_u32 s11, 1
	v_lshl_add_u64 v[6:7], s[8:9], 0, v[148:149]
	v_lshl_add_u64 v[4:5], s[8:9], 0, v[152:153]
	v_lshl_add_u64 v[0:1], s[6:7], 0, v[146:147]
	s_cselect_b64 s[0:1], -1, 0
	s_cmp_lg_u32 s11, 1
	v_lshl_add_u64 v[2:3], s[6:7], 0, v[150:151]
	s_mov_b64 s[22:23], 0x80
	s_setprio 1
	s_cbranch_scc1 .LBB0_467
	s_setprio 0
	s_barrier

; #define PG8_WAIT_V(n) asm volatile("s_waitcnt vmcnt(" #n ")" ::: "memory")
; #define PG8_BAR __builtin_amdgcn_s_barrier()
; template <class Epi, class Sched, bool ALIGN_EPI = false, bool SP2 = false>
; __device__ __forceinline__ void gemm_phase(PG8_LAS unsigned char* lds, const Gemm g, const Sched& S, const Epi& E) {
;     ...
;     PG8_WAIT_V(0);
;     if constexpr (!ALIGN_EPI) { if (wr == 0) PG8_BAR; }
;     PG8_BAR;
.LBB0_579:
	s_setprio 0
	s_waitcnt vmcnt(0)
	s_barrier
